# stick-breaking non-diagonal bodies: the exp-input clamp constant comes from an SGPR (s101) instead of a 32-bit literal in each of the 128 v_min (smaller code, same arithmetic)
# baseline (speedup 1.0000x reference)
; DI unsigned pk2(float lo, float hi) { f32x2 v = {lo, hi}; bf2_t r = __builtin_convertvector(v, bf2_t); return __builtin_bit_cast(unsigned, r); }
; DI void xhalf(float x, float& lo, float& hi) { const u32x2p r = __builtin_amdgcn_permlane32_swap(__float_as_uint(x), __float_as_uint(x), false, false); lo = __uint_as_float(r.x); hi = __uint_as_float(r.y); }
; #define MFMA32(a, b, c) __builtin_amdgcn_mfma_f32_32x32x16_bf16((a), (b), (c), 0, 0, 0)
; DI void sb_block2(const Params& p, LAS unsigned char* lds, int bh, int qb2, int tid) {
;     ...
; #pragma unroll
;                             for (int i = 15; i >= 0; --i) {
;                                 const float w = __builtin_amdgcn_exp2f(fminf(z[i], 86.f));
;                                 float be = __builtin_amdgcn_rcpf(1.f + w);
;                                 float om = w * be;
;                                 if (diag) { const bool valid = (16 * h + i < r); be = valid ? be : 0.f; om = valid ? om : 1.f; }
;                                 a[i] = be * tot;
;                                 tot *= om;
;                             }
;                             float tlo, thi; xhalf(tot, tlo, thi);
;                             const float bs = carry[g] * (h == 0 ? thi : 1.f);
;                             carry[g] *= tlo * thi;
; #pragma unroll
;                             for (int i = 0; i < 16; ++i) a[i] *= bs;
;                             bf16x8 pf[2];
; #pragma unroll
;                             for (int s2 = 0; s2 < 2; ++s2) {
;                                 u32x4 w; w.x = pk2(a[8 * s2 + 0], a[8 * s2 + 1]); w.y = pk2(a[8 * s2 + 2], a[8 * s2 + 3]); w.z = pk2(a[8 * s2 + 4], a[8 * s2 + 5]); w.w = pk2(a[8 * s2 + 6], a[8 * s2 + 7]);
;                                 pf[s2] = __builtin_bit_cast(bf16x8, w);
;                             }
; #pragma unroll
;                             for (int s2 = 0; s2 < 2; ++s2) { o0[g] = MFMA32(vf[s2], pf[s2], o0[g]); o1[g] = MFMA32(vf[2 + s2], pf[s2], o1[g]); }
.Lsb_lean_0:
	s_mov_b32 s101, 0x42ac0000
	v_min_f32_e32 v17, s101, v33
	v_exp_f32_e32 v17, v17
	v_min_f32_e32 v32, s101, v32
	v_exp_f32_e32 v32, v32
	v_add_f32_e32 v33, 1.0, v17
	v_rcp_f32_e32 v33, v33
	v_add_f32_e32 v50, 1.0, v32
	v_rcp_f32_e32 v50, v50
	v_min_f32_e32 v31, s101, v31
	v_exp_f32_e32 v31, v31
	v_mul_f32_e32 v17, v17, v33
	v_mul_f32_e32 v32, v32, v50
	v_add_f32_e32 v197, 1.0, v31
	v_rcp_f32_e32 v197, v197
	v_min_f32_e32 v30, s101, v30
	v_exp_f32_e32 v30, v30
	v_mov_b32_e32 v52, v32
	v_mul_f32_e32 v32, v50, v17
	v_mul_f32_e32 v31, v31, v197
	v_add_f32_e32 v198, 1.0, v30
	v_rcp_f32_e32 v198, v198
	v_min_f32_e32 v29, s101, v29
	v_exp_f32_e32 v29, v29
	v_mul_f32_e32 v17, v17, v52
	v_mul_f32_e32 v82, v197, v17
	v_mul_f32_e32 v17, v31, v17
	v_mul_f32_e32 v30, v30, v198
	v_add_f32_e32 v199, 1.0, v29
	v_rcp_f32_e32 v199, v199
	v_min_f32_e32 v28, s101, v28
	v_exp_f32_e32 v28, v28
	v_mul_f32_e32 v31, v198, v17
	v_mul_f32_e32 v17, v30, v17
	v_mul_f32_e32 v29, v29, v199
	v_add_f32_e32 v200, 1.0, v28
	v_rcp_f32_e32 v200, v200
	v_min_f32_e32 v27, s101, v27
	v_exp_f32_e32 v27, v27
	v_mul_f32_e32 v30, v199, v17
	v_mul_f32_e32 v17, v29, v17
	v_mul_f32_e32 v28, v28, v200
	v_add_f32_e32 v201, 1.0, v27
	v_rcp_f32_e32 v201, v201
	v_min_f32_e32 v26, s101, v26
	v_exp_f32_e32 v26, v26
	v_min_f32_e32 v25, s101, v25
	v_mul_f32_e32 v27, v27, v201
	v_exp_f32_e32 v25, v25
	v_mul_f32_e32 v29, v200, v17
	v_mul_f32_e32 v17, v28, v17
	v_add_f32_e32 v50, 1.0, v26
	v_rcp_f32_e32 v50, v50
	v_mul_f32_e32 v28, v201, v17
	v_mul_f32_e32 v17, v27, v17
	v_add_f32_e32 v27, 1.0, v25
	v_rcp_f32_e32 v27, v27
	v_min_f32_e32 v24, s101, v24
	v_exp_f32_e32 v24, v24
	v_mul_f32_e32 v26, v26, v50
	v_mul_f32_e32 v25, v25, v27
	v_add_f32_e32 v202, 1.0, v24
	v_rcp_f32_e32 v202, v202
	v_min_f32_e32 v23, s101, v23
	v_exp_f32_e32 v23, v23
	v_mul_f32_e32 v26, v26, v17
	v_mul_f32_e32 v27, v27, v26
	v_mul_f32_e32 v25, v25, v26
	v_mul_f32_e32 v24, v24, v202
	v_add_f32_e32 v203, 1.0, v23
	v_rcp_f32_e32 v203, v203
	v_min_f32_e32 v22, s101, v22
	v_exp_f32_e32 v22, v22
	v_mul_f32_e32 v26, v202, v25
	v_mul_f32_e32 v24, v24, v25
	v_mul_f32_e32 v23, v23, v203
	v_add_f32_e32 v204, 1.0, v22
	v_rcp_f32_e32 v204, v204
	v_min_f32_e32 v21, s101, v21
	v_exp_f32_e32 v21, v21
	v_mul_f32_e32 v25, v203, v24
	v_mul_f32_e32 v23, v23, v24
	v_mul_f32_e32 v22, v22, v204
	v_add_f32_e32 v205, 1.0, v21
	v_rcp_f32_e32 v205, v205
	v_min_f32_e32 v20, s101, v20
	v_exp_f32_e32 v20, v20
	v_mul_f32_e32 v24, v204, v23
	v_mul_f32_e32 v22, v22, v23
	v_mul_f32_e32 v21, v21, v205
	v_add_f32_e32 v206, 1.0, v20
	v_rcp_f32_e32 v206, v206
	v_min_f32_e32 v19, s101, v19
	v_exp_f32_e32 v19, v19
	v_mul_f32_e32 v23, v205, v22
	v_mul_f32_e32 v21, v21, v22
	v_mul_f32_e32 v20, v20, v206
	v_add_f32_e32 v207, 1.0, v19
	v_rcp_f32_e32 v207, v207
	v_min_f32_e32 v18, s101, v18
	v_exp_f32_e32 v18, v18
	v_mul_f32_e32 v52, v206, v21
	v_mul_f32_e32 v20, v20, v21
	v_mul_f32_e32 v19, v19, v207
	v_add_f32_e32 v51, 1.0, v18
	v_rcp_f32_e32 v51, v51
	v_mul_f32_e32 v19, v19, v20
	v_mul_f32_e32 v18, v18, v51
	v_mul_f32_e32 v83, v18, v19
	v_mul_f32_e32 v21, v207, v20
	v_mov_b32_e32 v84, v83
	v_mov_b32_e32 v20, v51
	s_nop 0
	v_permlane32_swap_b32_e32 v83, v84
	v_mul_f32_e32 v20, v20, v19
	v_cndmask_b32_e64 v22, 1.0, v84, s[10:11]
	v_mul_f32_e32 v18, v20, v22
	v_mul_f32_e32 v19, v21, v22
	v_mul_f32_e32 v20, v52, v22
	v_mul_f32_e32 v21, v23, v22
	v_mul_f32_e32 v23, v24, v22
	v_mul_f32_e32 v24, v25, v22
	v_mul_f32_e32 v25, v26, v22
	v_mul_f32_e32 v26, v27, v22
	v_cvt_pk_bf16_f32 v18, v18, v19
	v_cvt_pk_bf16_f32 v19, v20, v21
	v_cvt_pk_bf16_f32 v20, v23, v24
	v_cvt_pk_bf16_f32 v21, v25, v26
	v_mov_b32_e32 v23, v50
	s_nop 0
	v_mfma_f32_32x32x16_bf16 v[66:81], v[46:49], v[18:21], 0
	v_mul_f32_e32 v17, v23, v17
	v_mul_f32_e32 v17, v17, v22
	v_mul_f32_e32 v24, v28, v22
	v_mul_f32_e32 v25, v29, v22
	v_mul_f32_e32 v26, v30, v22
	v_mul_f32_e32 v190, v83, v84

; DI unsigned pk2(float lo, float hi) { f32x2 v = {lo, hi}; bf2_t r = __builtin_convertvector(v, bf2_t); return __builtin_bit_cast(unsigned, r); }
; DI void xhalf(float x, float& lo, float& hi) { const u32x2p r = __builtin_amdgcn_permlane32_swap(__float_as_uint(x), __float_as_uint(x), false, false); lo = __uint_as_float(r.x); hi = __uint_as_float(r.y); }
; #define MFMA32(a, b, c) __builtin_amdgcn_mfma_f32_32x32x16_bf16((a), (b), (c), 0, 0, 0)
; DI void sb_block2(const Params& p, LAS unsigned char* lds, int bh, int qb2, int tid) {
;     ...
;                             for (int i = 15; i >= 0; --i) {
;                                 const float w = __builtin_amdgcn_exp2f(fminf(z[i], 86.f));
;                                 float be = __builtin_amdgcn_rcpf(1.f + w);
;                                 float om = w * be;
;                                 if (diag) { const bool valid = (16 * h + i < r); be = valid ? be : 0.f; om = valid ? om : 1.f; }
;                                 a[i] = be * tot;
;                                 tot *= om;
;                             }
;                             float tlo, thi; xhalf(tot, tlo, thi);
;                             const float bs = carry[g] * (h == 0 ? thi : 1.f);
;                             carry[g] *= tlo * thi;
; #pragma unroll
;                             for (int i = 0; i < 16; ++i) a[i] *= bs;
;                             bf16x8 pf[2];
; #pragma unroll
;                             for (int s2 = 0; s2 < 2; ++s2) {
;                                 u32x4 w; w.x = pk2(a[8 * s2 + 0], a[8 * s2 + 1]); w.y = pk2(a[8 * s2 + 2], a[8 * s2 + 3]); w.z = pk2(a[8 * s2 + 4], a[8 * s2 + 5]); w.w = pk2(a[8 * s2 + 6], a[8 * s2 + 7]);
;                                 pf[s2] = __builtin_bit_cast(bf16x8, w);
;                             }
; #pragma unroll
;                             for (int s2 = 0; s2 < 2; ++s2) { o0[g] = MFMA32(vf[s2], pf[s2], o0[g]); o1[g] = MFMA32(vf[2 + s2], pf[s2], o1[g]); }
.Lsb_lean_1:
	s_mov_b32 s101, 0x42ac0000
	v_min_f32_e32 v15, s101, v15
	v_exp_f32_e32 v15, v15
	v_min_f32_e32 v14, s101, v14
	v_exp_f32_e32 v14, v14
	v_add_f32_e32 v17, 1.0, v15
	v_rcp_f32_e32 v17, v17
	v_add_f32_e32 v18, 1.0, v14
	v_rcp_f32_e32 v18, v18
	v_min_f32_e32 v13, s101, v13
	v_exp_f32_e32 v13, v13
	v_mul_f32_e32 v197, v15, v17
	v_mov_b32_e32 v15, v17
	v_mul_f32_e32 v14, v14, v18
	v_add_f32_e32 v198, 1.0, v13
	v_rcp_f32_e32 v198, v198
	v_min_f32_e32 v12, s101, v12
	v_exp_f32_e32 v12, v12
	v_mov_b32_e32 v20, v14
	v_mul_f32_e32 v14, v18, v197
	v_mul_f32_e32 v13, v13, v198
	v_add_f32_e32 v199, 1.0, v12
	v_rcp_f32_e32 v199, v199
	v_min_f32_e32 v11, s101, v11
	v_exp_f32_e32 v11, v11
	v_mul_f32_e32 v17, v197, v20
	v_mul_f32_e32 v18, v198, v17
	v_mul_f32_e32 v13, v13, v17
	v_mul_f32_e32 v12, v12, v199
	v_add_f32_e32 v200, 1.0, v11
	v_rcp_f32_e32 v200, v200
	v_min_f32_e32 v10, s101, v10
	v_exp_f32_e32 v10, v10
	v_mul_f32_e32 v17, v199, v13
	v_mul_f32_e32 v12, v12, v13
	v_mul_f32_e32 v11, v11, v200
	v_add_f32_e32 v201, 1.0, v10
	v_rcp_f32_e32 v201, v201
	v_min_f32_e32 v9, s101, v9
	v_exp_f32_e32 v9, v9
	v_mul_f32_e32 v13, v200, v12
	v_mul_f32_e32 v11, v11, v12
	v_mul_f32_e32 v10, v10, v201
	v_add_f32_e32 v202, 1.0, v9
	v_rcp_f32_e32 v202, v202
	v_min_f32_e32 v8, s101, v8
	v_exp_f32_e32 v8, v8
	v_min_f32_e32 v7, s101, v7
	v_exp_f32_e32 v7, v7
	v_mul_f32_e32 v12, v201, v11
	v_mul_f32_e32 v10, v10, v11
	v_mul_f32_e32 v9, v9, v202
	v_add_f32_e32 v19, 1.0, v8
	v_rcp_f32_e32 v19, v19
	v_mul_f32_e32 v11, v202, v10
	v_mul_f32_e32 v9, v9, v10
	v_add_f32_e32 v10, 1.0, v7
	v_rcp_f32_e32 v10, v10
	v_min_f32_e32 v6, s101, v6
	v_exp_f32_e32 v6, v6
	v_mul_f32_e32 v8, v8, v19
	v_mul_f32_e32 v7, v7, v10
	v_add_f32_e32 v203, 1.0, v6
	v_rcp_f32_e32 v203, v203
	v_min_f32_e32 v5, s101, v5
	v_exp_f32_e32 v5, v5
	v_mul_f32_e32 v8, v8, v9
	v_mul_f32_e32 v10, v10, v8
	v_mul_f32_e32 v7, v7, v8
	v_mul_f32_e32 v6, v6, v203
	v_add_f32_e32 v204, 1.0, v5
	v_rcp_f32_e32 v204, v204
	v_min_f32_e32 v4, s101, v4
	v_exp_f32_e32 v4, v4
	v_mul_f32_e32 v8, v203, v7
	v_mul_f32_e32 v6, v6, v7
	v_mul_f32_e32 v5, v5, v204
	v_add_f32_e32 v205, 1.0, v4
	v_rcp_f32_e32 v205, v205
	v_min_f32_e32 v3, s101, v3
	v_exp_f32_e32 v3, v3
	v_mul_f32_e32 v7, v204, v6
	v_mul_f32_e32 v5, v5, v6
	v_mul_f32_e32 v4, v4, v205
	v_add_f32_e32 v206, 1.0, v3
	v_rcp_f32_e32 v206, v206
	v_min_f32_e32 v2, s101, v2
	v_exp_f32_e32 v2, v2
	v_mul_f32_e32 v6, v205, v5
	v_mul_f32_e32 v4, v4, v5
	v_mul_f32_e32 v3, v3, v206
	v_add_f32_e32 v207, 1.0, v2
	v_rcp_f32_e32 v207, v207
	v_min_f32_e32 v1, s101, v1
	v_exp_f32_e32 v1, v1
	v_mul_f32_e32 v5, v206, v4
	v_mul_f32_e32 v3, v3, v4
	v_mul_f32_e32 v2, v2, v207
	v_add_f32_e32 v208, 1.0, v1
	v_rcp_f32_e32 v208, v208
	v_min_f32_e32 v0, s101, v0
	v_exp_f32_e32 v0, v0
	v_mul_f32_e32 v21, v207, v3
	v_mul_f32_e32 v2, v2, v3
	v_mul_f32_e32 v1, v1, v208
	v_add_f32_e32 v209, 1.0, v0
	v_rcp_f32_e32 v209, v209
	v_mul_f32_e32 v3, v208, v2
	v_mul_f32_e32 v0, v0, v209
	v_mul_f32_e32 v1, v1, v2
	v_mul_f32_e32 v20, v0, v1
	v_mov_b32_e32 v22, v20
	s_nop 1
	s_nop 0
	v_permlane32_swap_b32_e32 v20, v22
	v_mul_f32_e32 v2, v209, v1
	v_cndmask_b32_e64 v4, 1.0, v22, s[10:11]
	v_mul_f32_e32 v0, v2, v4
	v_mul_f32_e32 v1, v3, v4
	v_mul_f32_e32 v2, v21, v4
	v_mul_f32_e32 v3, v5, v4
	v_mul_f32_e32 v5, v6, v4
	v_mul_f32_e32 v6, v7, v4
	v_mul_f32_e32 v7, v8, v4
	v_mul_f32_e32 v8, v10, v4
	v_cvt_pk_bf16_f32 v0, v0, v1
	v_cvt_pk_bf16_f32 v1, v2, v3
	v_cvt_pk_bf16_f32 v2, v5, v6
	v_cvt_pk_bf16_f32 v3, v7, v8
	v_mov_b32_e32 v5, v19
	s_nop 0
	v_mfma_f32_32x32x16_bf16 v[98:113], v[46:49], v[0:3], 0
	v_mul_f32_e32 v5, v5, v9
	v_mul_f32_e32 v6, v5, v4
	v_mul_f32_e32 v7, v11, v4
	v_mul_f32_e32 v8, v12, v4
	v_mul_f32_e32 v9, v13, v4
	v_mul_f32_e32 v191, v20, v22

; DI unsigned pk2(float lo, float hi) { f32x2 v = {lo, hi}; bf2_t r = __builtin_convertvector(v, bf2_t); return __builtin_bit_cast(unsigned, r); }
; DI void xhalf(float x, float& lo, float& hi) { const u32x2p r = __builtin_amdgcn_permlane32_swap(__float_as_uint(x), __float_as_uint(x), false, false); lo = __uint_as_float(r.x); hi = __uint_as_float(r.y); }
; #define MFMA32(a, b, c) __builtin_amdgcn_mfma_f32_32x32x16_bf16((a), (b), (c), 0, 0, 0)
; DI void sb_block2(const Params& p, LAS unsigned char* lds, int bh, int qb2, int tid) {
;     ...
;                             for (int i = 15; i >= 0; --i) {
;                                 const float w = __builtin_amdgcn_exp2f(fminf(z[i], 86.f));
;                                 float be = __builtin_amdgcn_rcpf(1.f + w);
;                                 float om = w * be;
;                                 if (diag) { const bool valid = (16 * h + i < r); be = valid ? be : 0.f; om = valid ? om : 1.f; }
;                                 a[i] = be * tot;
;                                 tot *= om;
;                             }
;                             float tlo, thi; xhalf(tot, tlo, thi);
;                             const float bs = carry[g] * (h == 0 ? thi : 1.f);
;                             carry[g] *= tlo * thi;
; #pragma unroll
;                             for (int i = 0; i < 16; ++i) a[i] *= bs;
;                             bf16x8 pf[2];
; #pragma unroll
;                             for (int s2 = 0; s2 < 2; ++s2) {
;                                 u32x4 w; w.x = pk2(a[8 * s2 + 0], a[8 * s2 + 1]); w.y = pk2(a[8 * s2 + 2], a[8 * s2 + 3]); w.z = pk2(a[8 * s2 + 4], a[8 * s2 + 5]); w.w = pk2(a[8 * s2 + 6], a[8 * s2 + 7]);
;                                 pf[s2] = __builtin_bit_cast(bf16x8, w);
;                             }
; #pragma unroll
;                             for (int s2 = 0; s2 < 2; ++s2) { o0[g] = MFMA32(vf[s2], pf[s2], o0[g]); o1[g] = MFMA32(vf[2 + s2], pf[s2], o1[g]); }
.Lsb_lean_2:
	s_mov_b32 s101, 0x42ac0000
	v_min_f32_e32 v197, s101, v49
	v_exp_f32_e32 v197, v197
	v_min_f32_e32 v1, s101, v48
	v_exp_f32_e32 v2, v1
	v_add_f32_e32 v1, 1.0, v197
	v_rcp_f32_e32 v1, v1
	v_add_f32_e32 v3, 1.0, v2
	v_rcp_f32_e32 v3, v3
	v_mul_f32_e32 v197, v197, v1
	v_mul_f32_e32 v198, v2, v3
	v_min_f32_e32 v2, s101, v47
	v_exp_f32_e32 v2, v2
	s_nop 0
	v_add_f32_e32 v5, 1.0, v2
	v_mul_f32_e32 v0, v3, v197
	v_mul_f32_e32 v3, v197, v198
	v_rcp_f32_e32 v5, v5
	v_min_f32_e32 v4, s101, v46
	v_exp_f32_e32 v4, v4
	v_mul_f32_e32 v2, v2, v5
	v_add_f32_e32 v199, 1.0, v4
	v_rcp_f32_e32 v199, v199
	v_mul_f32_e32 v7, v5, v3
	v_mul_f32_e32 v2, v2, v3
	v_mul_f32_e32 v3, v4, v199
	v_min_f32_e32 v4, s101, v45
	v_exp_f32_e32 v4, v4
	s_nop 0
	v_add_f32_e32 v200, 1.0, v4
	v_rcp_f32_e32 v200, v200
	v_mul_f32_e32 v8, v199, v2
	v_mul_f32_e32 v2, v3, v2
	v_mul_f32_e32 v3, v4, v200
	v_min_f32_e32 v4, s101, v44
	v_exp_f32_e32 v4, v4
	s_nop 0
	v_add_f32_e32 v201, 1.0, v4
	v_rcp_f32_e32 v201, v201
	v_mul_f32_e32 v9, v200, v2
	v_mul_f32_e32 v2, v3, v2
	v_mul_f32_e32 v3, v4, v201
	v_min_f32_e32 v4, s101, v43
	v_exp_f32_e32 v4, v4
	s_nop 0
	v_add_f32_e32 v202, 1.0, v4
	v_mul_f32_e32 v10, v201, v2
	v_rcp_f32_e32 v202, v202
	v_min_f32_e32 v5, s101, v42
	v_exp_f32_e32 v5, v5
	v_mul_f32_e32 v2, v3, v2
	v_mul_f32_e32 v3, v4, v202
	v_add_f32_e32 v6, 1.0, v5
	v_rcp_f32_e32 v11, v6
	v_min_f32_e32 v6, s101, v41
	v_exp_f32_e32 v6, v6
	v_mul_f32_e32 v12, v202, v2
	v_mul_f32_e32 v13, v3, v2
	v_mul_f32_e32 v2, v5, v11
	v_add_f32_e32 v3, 1.0, v6
	v_rcp_f32_e32 v3, v3
	v_min_f32_e32 v5, s101, v40
	v_exp_f32_e32 v5, v5
	v_mul_f32_e32 v4, v6, v3
	v_add_f32_e32 v6, 1.0, v5
	v_rcp_f32_e32 v6, v6
	v_mul_f32_e32 v2, v2, v13
	v_mul_f32_e32 v3, v3, v2
	v_mul_f32_e32 v2, v4, v2
	v_mul_f32_e32 v4, v5, v6
	v_min_f32_e32 v5, s101, v39
	v_exp_f32_e32 v5, v5
	s_nop 0
	v_add_f32_e32 v203, 1.0, v5
	v_rcp_f32_e32 v203, v203
	v_mul_f32_e32 v15, v6, v2
	v_mul_f32_e32 v2, v4, v2
	v_mul_f32_e32 v4, v5, v203
	v_min_f32_e32 v5, s101, v38
	v_exp_f32_e32 v5, v5
	s_nop 0
	v_add_f32_e32 v204, 1.0, v5
	v_rcp_f32_e32 v204, v204
	v_mul_f32_e32 v17, v203, v2
	v_mul_f32_e32 v2, v4, v2
	v_mul_f32_e32 v4, v5, v204
	v_min_f32_e32 v5, s101, v37
	v_exp_f32_e32 v5, v5
	s_nop 0
	v_add_f32_e32 v205, 1.0, v5
	v_rcp_f32_e32 v205, v205
	v_mul_f32_e32 v18, v204, v2
	v_mul_f32_e32 v2, v4, v2
	v_mul_f32_e32 v4, v5, v205
	v_min_f32_e32 v5, s101, v36
	v_exp_f32_e32 v5, v5
	s_nop 0
	v_add_f32_e32 v206, 1.0, v5
	v_rcp_f32_e32 v206, v206
	v_mul_f32_e32 v19, v205, v2
	v_mul_f32_e32 v2, v4, v2
	v_mul_f32_e32 v4, v5, v206
	v_min_f32_e32 v5, s101, v35
	v_exp_f32_e32 v5, v5
	s_nop 0
	v_add_f32_e32 v207, 1.0, v5
	v_rcp_f32_e32 v207, v207
	v_mul_f32_e32 v20, v206, v2
	v_mul_f32_e32 v2, v4, v2
	v_mul_f32_e32 v4, v5, v207
	v_min_f32_e32 v5, s101, v34
	v_exp_f32_e32 v5, v5
	s_nop 0
	v_add_f32_e32 v208, 1.0, v5
	v_rcp_f32_e32 v208, v208
	v_mul_f32_e32 v21, v207, v2
	v_mul_f32_e32 v2, v4, v2
	v_mul_f32_e32 v4, v5, v208
	v_mul_f32_e32 v14, v4, v2
	v_mov_b32_e32 v22, v14
	s_nop 1
	s_nop 0
	v_permlane32_swap_b32_e32 v14, v22
	v_mul_f32_e32 v5, v208, v2
	v_cndmask_b32_e64 v2, 1.0, v22, s[10:11]
	v_mul_f32_e32 v6, v191, v2
	v_mul_f32_e32 v2, v5, v6
	v_mul_f32_e32 v4, v21, v6
	v_mul_f32_e32 v5, v20, v6
	v_mul_f32_e32 v19, v19, v6
	v_mul_f32_e32 v18, v18, v6
	v_mul_f32_e32 v17, v17, v6
	v_mul_f32_e32 v15, v15, v6
	v_mul_f32_e32 v20, v3, v6
	v_cvt_pk_bf16_f32 v2, v2, v4
	v_cvt_pk_bf16_f32 v3, v5, v19
	v_cvt_pk_bf16_f32 v4, v18, v17
	v_cvt_pk_bf16_f32 v5, v15, v20
	v_cndmask_b32_e64 v15, 0, v11, s[28:29]
	s_waitcnt lgkmcnt(0)
	v_mfma_f32_32x32x16_bf16 v[98:113], v[158:161], v[2:5], v[98:113]
	v_mul_f32_e32 v11, v11, v13
	v_mul_f32_e32 v11, v11, v6
	v_mul_f32_e32 v12, v12, v6
	v_mul_f32_e32 v10, v10, v6
	v_mul_f32_e32 v9, v9, v6
	v_mfma_f32_32x32x16_bf16 v[82:97], v[154:157], v[2:5], v[82:97]
	v_mul_f32_e32 v2, v8, v6
	v_mul_f32_e32 v3, v7, v6
	v_mul_f32_e64 v4, v0, v6
	v_mul_f32_e64 v5, v1, v6
	v_cvt_pk_bf16_f32 v0, v11, v12
	v_cvt_pk_bf16_f32 v1, v10, v9
	v_cvt_pk_bf16_f32 v2, v2, v3
	v_cvt_pk_bf16_f32 v3, v4, v5
	v_mul_f32_e32 v4, v14, v22
	v_mul_f32_e32 v191, v191, v4
	v_mfma_f32_32x32x16_bf16 v[98:113], v[150:153], v[0:3], v[98:113]

; DI unsigned pk2(float lo, float hi) { f32x2 v = {lo, hi}; bf2_t r = __builtin_convertvector(v, bf2_t); return __builtin_bit_cast(unsigned, r); }
; DI void xhalf(float x, float& lo, float& hi) { const u32x2p r = __builtin_amdgcn_permlane32_swap(__float_as_uint(x), __float_as_uint(x), false, false); lo = __uint_as_float(r.x); hi = __uint_as_float(r.y); }
; #define MFMA32(a, b, c) __builtin_amdgcn_mfma_f32_32x32x16_bf16((a), (b), (c), 0, 0, 0)
; DI void sb_block2(const Params& p, LAS unsigned char* lds, int bh, int qb2, int tid) {
;     ...
;                             for (int i = 15; i >= 0; --i) {
;                                 const float w = __builtin_amdgcn_exp2f(fminf(z[i], 86.f));
;                                 float be = __builtin_amdgcn_rcpf(1.f + w);
;                                 float om = w * be;
;                                 if (diag) { const bool valid = (16 * h + i < r); be = valid ? be : 0.f; om = valid ? om : 1.f; }
;                                 a[i] = be * tot;
;                                 tot *= om;
;                             }
;                             float tlo, thi; xhalf(tot, tlo, thi);
;                             const float bs = carry[g] * (h == 0 ? thi : 1.f);
;                             carry[g] *= tlo * thi;
; #pragma unroll
;                             for (int i = 0; i < 16; ++i) a[i] *= bs;
;                             bf16x8 pf[2];
; #pragma unroll
;                             for (int s2 = 0; s2 < 2; ++s2) {
;                                 u32x4 w; w.x = pk2(a[8 * s2 + 0], a[8 * s2 + 1]); w.y = pk2(a[8 * s2 + 2], a[8 * s2 + 3]); w.z = pk2(a[8 * s2 + 4], a[8 * s2 + 5]); w.w = pk2(a[8 * s2 + 6], a[8 * s2 + 7]);
;                                 pf[s2] = __builtin_bit_cast(bf16x8, w);
;                             }
; #pragma unroll
;                             for (int s2 = 0; s2 < 2; ++s2) { o0[g] = MFMA32(vf[s2], pf[s2], o0[g]); o1[g] = MFMA32(vf[2 + s2], pf[s2], o1[g]); }
.Lsb_lean_4:
	s_mov_b32 s101, 0x42ac0000
	v_min_f32_e32 v197, s101, v33
	v_exp_f32_e32 v197, v197
	v_min_f32_e32 v1, s101, v32
	v_exp_f32_e32 v2, v1
	v_add_f32_e32 v1, 1.0, v197
	v_rcp_f32_e32 v1, v1
	v_add_f32_e32 v3, 1.0, v2
	v_rcp_f32_e32 v3, v3
	v_mul_f32_e32 v197, v197, v1
	v_mul_f32_e32 v198, v2, v3
	v_min_f32_e32 v2, s101, v31
	v_exp_f32_e32 v2, v2
	s_nop 0
	v_add_f32_e32 v5, 1.0, v2
	v_mul_f32_e32 v0, v3, v197
	v_mul_f32_e32 v3, v197, v198
	v_rcp_f32_e32 v5, v5
	v_min_f32_e32 v4, s101, v30
	v_exp_f32_e32 v4, v4
	v_mul_f32_e32 v2, v2, v5
	v_add_f32_e32 v199, 1.0, v4
	v_rcp_f32_e32 v199, v199
	v_mul_f32_e32 v7, v5, v3
	v_mul_f32_e32 v2, v2, v3
	v_mul_f32_e32 v3, v4, v199
	v_min_f32_e32 v4, s101, v29
	v_exp_f32_e32 v4, v4
	s_nop 0
	v_add_f32_e32 v200, 1.0, v4
	v_rcp_f32_e32 v200, v200
	v_mul_f32_e32 v8, v199, v2
	v_mul_f32_e32 v2, v3, v2
	v_mul_f32_e32 v3, v4, v200
	v_min_f32_e32 v4, s101, v28
	v_exp_f32_e32 v4, v4
	s_nop 0
	v_add_f32_e32 v201, 1.0, v4
	v_rcp_f32_e32 v201, v201
	v_mul_f32_e32 v9, v200, v2
	v_mul_f32_e32 v2, v3, v2
	v_mul_f32_e32 v3, v4, v201
	v_min_f32_e32 v4, s101, v27
	v_exp_f32_e32 v4, v4
	s_nop 0
	v_add_f32_e32 v202, 1.0, v4
	v_mul_f32_e32 v10, v201, v2
	v_rcp_f32_e32 v202, v202
	v_min_f32_e32 v5, s101, v26
	v_exp_f32_e32 v5, v5
	v_mul_f32_e32 v2, v3, v2
	v_mul_f32_e32 v3, v4, v202
	v_add_f32_e32 v6, 1.0, v5
	v_rcp_f32_e32 v11, v6
	v_min_f32_e32 v6, s101, v25
	v_exp_f32_e32 v6, v6
	v_mul_f32_e32 v12, v202, v2
	v_mul_f32_e32 v13, v3, v2
	v_mul_f32_e32 v2, v5, v11
	v_add_f32_e32 v3, 1.0, v6
	v_rcp_f32_e32 v3, v3
	v_min_f32_e32 v5, s101, v24
	v_exp_f32_e32 v5, v5
	v_mul_f32_e32 v4, v6, v3
	v_add_f32_e32 v6, 1.0, v5
	v_rcp_f32_e32 v6, v6
	v_mul_f32_e32 v2, v2, v13
	v_mul_f32_e32 v3, v3, v2
	v_mul_f32_e32 v2, v4, v2
	v_mul_f32_e32 v4, v5, v6
	v_min_f32_e32 v5, s101, v23
	v_exp_f32_e32 v5, v5
	s_nop 0
	v_add_f32_e32 v203, 1.0, v5
	v_rcp_f32_e32 v203, v203
	v_mul_f32_e32 v15, v6, v2
	v_mul_f32_e32 v2, v4, v2
	v_mul_f32_e32 v4, v5, v203
	v_min_f32_e32 v5, s101, v22
	v_exp_f32_e32 v5, v5
	s_nop 0
	v_add_f32_e32 v204, 1.0, v5
	v_rcp_f32_e32 v204, v204
	v_mul_f32_e32 v17, v203, v2
	v_mul_f32_e32 v2, v4, v2
	v_mul_f32_e32 v4, v5, v204
	v_min_f32_e32 v5, s101, v21
	v_exp_f32_e32 v5, v5
	s_nop 0
	v_add_f32_e32 v205, 1.0, v5
	v_rcp_f32_e32 v205, v205
	v_mul_f32_e32 v21, v204, v2
	v_mul_f32_e32 v2, v4, v2
	v_mul_f32_e32 v4, v5, v205
	v_min_f32_e32 v5, s101, v20
	v_exp_f32_e32 v5, v5
	s_nop 0
	v_add_f32_e32 v206, 1.0, v5
	v_rcp_f32_e32 v206, v206
	v_mul_f32_e32 v20, v205, v2
	v_mul_f32_e32 v2, v4, v2
	v_mul_f32_e32 v4, v5, v206
	v_min_f32_e32 v5, s101, v19
	v_exp_f32_e32 v5, v5
	s_nop 0
	v_add_f32_e32 v207, 1.0, v5
	v_rcp_f32_e32 v207, v207
	v_mul_f32_e32 v19, v206, v2
	v_mul_f32_e32 v2, v4, v2
	v_mul_f32_e32 v4, v5, v207
	v_min_f32_e32 v5, s101, v18
	v_exp_f32_e32 v5, v5
	s_nop 0
	v_add_f32_e32 v208, 1.0, v5
	v_rcp_f32_e32 v208, v208
	v_mul_f32_e32 v18, v207, v2
	v_mul_f32_e32 v2, v4, v2
	v_mul_f32_e32 v4, v5, v208
	v_mul_f32_e32 v14, v4, v2
	v_mov_b32_e32 v22, v14
	s_nop 1
	s_nop 0
	v_permlane32_swap_b32_e32 v14, v22
	v_mul_f32_e32 v5, v208, v2
	v_cndmask_b32_e64 v2, 1.0, v22, s[10:11]
	v_mul_f32_e32 v6, v190, v2
	v_mul_f32_e32 v2, v5, v6
	v_mul_f32_e32 v4, v18, v6
	v_mul_f32_e32 v5, v19, v6
	v_mul_f32_e32 v18, v20, v6
	v_mul_f32_e32 v19, v21, v6
	v_mul_f32_e32 v17, v17, v6
	v_mul_f32_e32 v15, v15, v6
	v_mul_f32_e32 v20, v3, v6
	v_cvt_pk_bf16_f32 v2, v2, v4
	v_cvt_pk_bf16_f32 v3, v5, v18
	v_cvt_pk_bf16_f32 v4, v19, v17
	v_cvt_pk_bf16_f32 v5, v15, v20
	v_cndmask_b32_e64 v15, 0, v11, s[28:29]
	s_waitcnt lgkmcnt(0)
	v_mfma_f32_32x32x16_bf16 v[66:81], v[158:161], v[2:5], v[66:81]
	v_mul_f32_e32 v11, v11, v13
	v_mul_f32_e32 v11, v11, v6
	v_mul_f32_e32 v12, v12, v6
	v_mul_f32_e32 v10, v10, v6
	v_mul_f32_e32 v9, v9, v6
	v_mfma_f32_32x32x16_bf16 v[50:65], v[154:157], v[2:5], v[50:65]
	v_mul_f32_e32 v2, v8, v6
	v_mul_f32_e32 v3, v7, v6
	v_mul_f32_e64 v4, v0, v6
	v_mul_f32_e64 v5, v1, v6
	v_cvt_pk_bf16_f32 v0, v11, v12
	v_cvt_pk_bf16_f32 v1, v10, v9
	v_cvt_pk_bf16_f32 v2, v2, v3
	v_cvt_pk_bf16_f32 v3, v4, v5
	v_mul_f32_e32 v4, v14, v22
	v_mul_f32_e32 v190, v190, v4
	v_mfma_f32_32x32x16_bf16 v[66:81], v[150:153], v[0:3], v[66:81]
